# stack of the latency-chain edits: attention finalize loads ahead + lambda dot products per lane + out-phase epilogue loads grouped + phase_o parameter loads early, on top of the best version
# speedup vs baseline: 1.0004x; 1.0004x over previous
; DI void attn_item(const Params& p, int l, int item, char* lds) {
;     ...
;   if (m == 0) {
;     float d1 = 0.f, d2 = 0.f;
;     for (int i = 0; i < 64; ++i) { d1 += p.lq1[l * 64 + i] * p.lk1[l * 64 + i]; d2 += p.lq2[l * 64 + i] * p.lk2[l * 64 + i]; }
;     const float lam_init = 0.8f - 0.6f * __expf(-0.3f * (float)l);
;     const float lam = __expf(d1) - __expf(d2) + lam_init;
;     float ss = 0.f;
; #pragma unroll
;     for (int vt = 0; vt < 4; ++vt)
; #pragma unroll
;       for (int e = 0; e < 16; ++e) {
;         const int vd = vt * 32 + (e & 3) + 8 * (e >> 2) + 4 * hh;
;         const float o2 = xb[(qh * 128 + vd) * 32 + q];
;         const float o = O[vt][e] - lam * o2; O[vt][e] = o; ss += o * o;
;       }
;     ss += __shfl_xor(ss, 32);
.LBB0_609:
	s_andn2_b64 vcc, exec, s[0:1]
	s_waitcnt lgkmcnt(0)
	s_barrier
	s_cbranch_vccnz .LBB0_571
	v_readlane_b32 s68, v251, 33
	v_readlane_b32 s72, v251, 37
	v_readlane_b32 s73, v251, 38
	v_readlane_b32 s74, v251, 39
	v_readlane_b32 s75, v251, 40
	v_readlane_b32 s76, v251, 41
	v_readlane_b32 s77, v251, 42
	v_readlane_b32 s78, v251, 43
	v_readlane_b32 s79, v251, 44
	v_readlane_b32 s80, v251, 45
	v_readlane_b32 s81, v251, 46
	v_readlane_b32 s82, v251, 47
	v_readlane_b32 s83, v251, 48
	s_mov_b32 s30, s87
	s_mov_b32 s27, s86
	s_mov_b32 s26, s85
	s_mov_b32 s21, s84
	v_readlane_b32 s72, v252, 3
	s_mov_b64 s[0:1], 0
	v_mov_b32_e32 v21, 0
	v_mov_b32_e32 v20, 0
	v_readlane_b32 s69, v251, 34
	v_readlane_b32 s70, v251, 35
	v_readlane_b32 s71, v251, 36
	v_readlane_b32 s84, v252, 15
	v_readlane_b32 s85, v252, 16
	v_readlane_b32 s86, v252, 17
	v_readlane_b32 s87, v252, 18
	v_readlane_b32 s73, v252, 4
	v_readlane_b32 s74, v252, 5
	v_readlane_b32 s75, v252, 6
	v_readlane_b32 s76, v252, 7
	v_readlane_b32 s77, v252, 8
	v_readlane_b32 s78, v252, 9
	v_readlane_b32 s79, v252, 10
	v_readlane_b32 s80, v252, 11
	v_readlane_b32 s81, v252, 12
	v_readlane_b32 s82, v252, 13
	v_readlane_b32 s83, v252, 14
	v_lshlrev_b32_e32 v24, 2, v163
	v_lshl_or_b32 v24, v169, 7, v24
	global_load_dword v25, v24, s[84:85]
	global_load_dword v26, v24, s[86:87]
	global_load_dword v27, v24, s[68:69]
	global_load_dword v28, v24, s[70:71]
	s_waitcnt vmcnt(0)
	v_mul_f32_e32 v21, v25, v26
	v_mul_f32_e32 v20, v27, v28
	v_xor_b32_e32 v25, 4, v24
	ds_bpermute_b32 v26, v25, v20
	ds_bpermute_b32 v27, v25, v21
	s_waitcnt lgkmcnt(0)
	v_add_f32_e32 v20, v20, v26
	v_add_f32_e32 v21, v21, v27
	v_xor_b32_e32 v25, 8, v24
	ds_bpermute_b32 v26, v25, v20
	ds_bpermute_b32 v27, v25, v21
	s_waitcnt lgkmcnt(0)
	v_add_f32_e32 v20, v20, v26
	v_add_f32_e32 v21, v21, v27
	v_xor_b32_e32 v25, 16, v24
	ds_bpermute_b32 v26, v25, v20
	ds_bpermute_b32 v27, v25, v21
	s_waitcnt lgkmcnt(0)
	v_add_f32_e32 v20, v20, v26
	v_add_f32_e32 v21, v21, v27
	v_xor_b32_e32 v25, 32, v24
	ds_bpermute_b32 v26, v25, v20
	ds_bpermute_b32 v27, v25, v21
	s_waitcnt lgkmcnt(0)
	v_add_f32_e32 v20, v20, v26
	v_add_f32_e32 v21, v21, v27
	v_xor_b32_e32 v25, 64, v24
	ds_bpermute_b32 v26, v25, v20
	ds_bpermute_b32 v27, v25, v21
	s_waitcnt lgkmcnt(0)
	v_add_f32_e32 v20, v20, v26
	v_add_f32_e32 v21, v21, v27
	v_xor_b32_e32 v25, 128, v24
	ds_bpermute_b32 v26, v25, v20
	ds_bpermute_b32 v27, v25, v21
	s_waitcnt lgkmcnt(0)
	v_add_f32_e32 v20, v20, v26
	v_add_f32_e32 v21, v21, v27
	v_mul_f32_e32 v0, 0x3fb8aa3b, v21
	v_mul_f32_e32 v20, 0x3fb8aa3b, v20
	v_exp_f32_e32 v0, v0
	v_exp_f32_e32 v20, v20
	s_and_b32 s0, s20, 0x1ffff80
	s_lshl_b32 s0, s0, 7
	s_mov_b32 s25, s97
	v_sub_f32_e32 v0, v0, v20
	v_lshl_or_b32 v20, v169, 9, s0
	v_lshl_or_b32 v91, v163, 2, v20
	v_add_u32_e32 v20, 0x400, v91
	ds_read2_b32 v[24:25], v91 offset1:32
	ds_read2_b32 v[26:27], v91 offset0:64 offset1:96
	ds_read2_b32 v[28:29], v20 offset1:32
	ds_read2_b32 v[30:31], v20 offset0:64 offset1:96
	v_add_u32_e32 v20, 0x800, v91
	ds_read2_b32 v[40:41], v20 offset1:32
	ds_read2_b32 v[42:43], v20 offset0:64 offset1:96
	v_add_u32_e32 v20, 0xc00, v91
	ds_read2_b32 v[44:45], v20 offset1:32
	ds_read2_b32 v[46:47], v20 offset0:64 offset1:96
	v_add_u32_e32 v20, 0x1000, v91
	ds_read2_b32 v[60:61], v20 offset1:32
	ds_read2_b32 v[62:63], v20 offset0:64 offset1:96
	v_add_u32_e32 v20, 0x1400, v91
	ds_read2_b32 v[78:79], v20 offset1:32
	ds_read2_b32 v[96:97], v20 offset0:64 offset1:96
	v_add_u32_e32 v20, 0x1800, v91
	ds_read2_b32 v[98:99], v20 offset1:32
	ds_read2_b32 v[100:101], v20 offset0:64 offset1:96
	v_add_u32_e32 v20, 0x1c00, v91
	ds_read2_b32 v[102:103], v20 offset1:32
	ds_read2_b32 v[104:105], v20 offset0:64 offset1:96
	v_add_u32_e32 v20, 0x2000, v91
	ds_read2_b32 v[106:107], v20 offset1:32
	ds_read2_b32 v[108:109], v20 offset0:64 offset1:96
	v_add_u32_e32 v20, 0x2400, v91
	ds_read2_b32 v[110:111], v20 offset1:32
	ds_read2_b32 v[112:113], v20 offset0:64 offset1:96
	v_add_u32_e32 v20, 0x2800, v91
	ds_read2_b32 v[114:115], v20 offset1:32
	ds_read2_b32 v[116:117], v20 offset0:64 offset1:96
	v_add_u32_e32 v20, 0x2c00, v91
	ds_read2_b32 v[118:119], v20 offset1:32
	ds_read2_b32 v[120:121], v20 offset0:64 offset1:96
	v_add_u32_e32 v20, 0x3000, v91
	ds_read2_b32 v[122:123], v20 offset1:32
	ds_read2_b32 v[124:125], v20 offset0:64 offset1:96
	v_add_u32_e32 v20, 0x3400, v91
	v_add_u32_e32 v92, 0x3c00, v91
	ds_read2_b32 v[126:127], v20 offset1:32
	ds_read2_b32 v[128:129], v20 offset0:64 offset1:96
	ds_read2_b32 v[20:21], v92 offset1:32
	v_add_u32_e32 v91, 0x3800, v91
	ds_read2_b32 v[92:93], v92 offset0:64 offset1:96
	ds_read2_b32 v[130:131], v91 offset1:32
	ds_read2_b32 v[132:133], v91 offset0:64 offset1:96
	v_add_f32_e32 v0, v190, v0
	v_mov_b32_e32 v169, v1
	s_waitcnt lgkmcnt(3)
	v_pk_fma_f32 v[20:21], v[0:1], v[20:21], v[18:19] op_sel_hi:[0,1,1] neg_lo:[1,0,0] neg_hi:[1,0,0]
	s_waitcnt lgkmcnt(2)
; DI void attn_item(const Params& p, int l, int item, char* lds) {
;     ...
; #pragma unroll
;     for (int vt = 0; vt < 4; ++vt)
; #pragma unroll
;       for (int e = 0; e < 16; ++e) {
;         const int vd = vt * 32 + (e & 3) + 8 * (e >> 2) + 4 * hh;
;         const float o2 = xb[(qh * 128 + vd) * 32 + q];
;         const float o = O[vt][e] - lam * o2; O[vt][e] = o; ss += o * o;
;       }
;     ss += __shfl_xor(ss, 32);
;     const float rstd = rsqrtf(ss * (1.0f / 128.0f) + 1e-5f) * (1.0f - lam_init);
;     const size_t row = (size_t)(qrow0 + qh * 32 + q);
;     const float* sg = p.subln_g + l * 128;
; #pragma unroll
;     for (int vt = 0; vt < 4; ++vt)
; #pragma unroll
;       for (int e4 = 0; e4 < 4; ++e4) {
;         const int vd = vt * 32 + 8 * e4 + 4 * hh;
;         const u32x2 gu = *(const u32x2*)(p.z + row * NZ + C_GA + h * 128 + vd);
;         const f32x4 gv = *(const f32x4*)(sg + vd);
	v_pk_fma_f32 v[18:19], v[0:1], v[92:93], v[22:23] op_sel_hi:[0,1,1] neg_lo:[1,0,0] neg_hi:[1,0,0]
	v_lshl_add_u64 v[22:23], v[164:165], 0, s[24:25]
	v_lshl_add_u64 v[92:93], v[22:23], 0, v[168:169]
	s_mov_b64 s[0:1], 0x1d00
	v_lshl_add_u64 v[22:23], v[92:93], 0, s[0:1]
	s_movk_i32 s0, 0x1000
	v_add_co_u32_e32 v92, vcc, s0, v92
	v_pk_fma_f32 v[86:87], v[0:1], v[24:25], v[86:87] op_sel_hi:[0,1,1] neg_lo:[1,0,0] neg_hi:[1,0,0]
	s_nop 0
	v_addc_co_u32_e32 v93, vcc, 0, v93, vcc
	v_pk_fma_f32 v[88:89], v[0:1], v[26:27], v[88:89] op_sel_hi:[0,1,1] neg_lo:[1,0,0] neg_hi:[1,0,0]
	v_pk_mul_f32 v[144:145], v[86:87], v[86:87]
	global_load_dwordx2 v[140:141], v[92:93], off offset:3328
	s_nop 0
	global_load_dwordx4 v[92:95], v162, s[22:23]
	global_load_dwordx4 v[222:225], v162, s[22:23] offset:32
	global_load_dwordx2 v[228:229], v[22:23], off offset:16
	v_pk_mul_f32 v[142:143], v[88:89], v[88:89]
	v_pk_fma_f32 v[84:85], v[0:1], v[30:31], v[84:85] op_sel_hi:[0,1,1] neg_lo:[1,0,0] neg_hi:[1,0,0]
	v_pk_fma_f32 v[80:81], v[0:1], v[28:29], v[80:81] op_sel_hi:[0,1,1] neg_lo:[1,0,0] neg_hi:[1,0,0]
	v_pk_fma_f32 v[82:83], v[0:1], v[42:43], v[82:83] op_sel_hi:[0,1,1] neg_lo:[1,0,0] neg_hi:[1,0,0]
	v_pk_fma_f32 v[70:71], v[0:1], v[40:41], v[70:71] op_sel_hi:[0,1,1] neg_lo:[1,0,0] neg_hi:[1,0,0]
	v_pk_fma_f32 v[76:77], v[0:1], v[46:47], v[76:77] op_sel_hi:[0,1,1] neg_lo:[1,0,0] neg_hi:[1,0,0]
	v_pk_fma_f32 v[156:157], v[0:1], v[44:45], v[68:69] op_sel_hi:[0,1,1] neg_lo:[1,0,0] neg_hi:[1,0,0]
	v_pk_fma_f32 v[68:69], v[0:1], v[62:63], v[74:75] op_sel_hi:[0,1,1] neg_lo:[1,0,0] neg_hi:[1,0,0]
	v_pk_fma_f32 v[66:67], v[0:1], v[60:61], v[66:67] op_sel_hi:[0,1,1] neg_lo:[1,0,0] neg_hi:[1,0,0]
	v_pk_fma_f32 v[60:61], v[0:1], v[96:97], v[72:73] op_sel_hi:[0,1,1] neg_lo:[1,0,0] neg_hi:[1,0,0]
	v_pk_fma_f32 v[62:63], v[0:1], v[78:79], v[64:65] op_sel_hi:[0,1,1] neg_lo:[1,0,0] neg_hi:[1,0,0]
	v_pk_fma_f32 v[58:59], v[0:1], v[100:101], v[58:59] op_sel_hi:[0,1,1] neg_lo:[1,0,0] neg_hi:[1,0,0]
	v_pk_fma_f32 v[52:53], v[0:1], v[98:99], v[52:53] op_sel_hi:[0,1,1] neg_lo:[1,0,0] neg_hi:[1,0,0]
	v_pk_fma_f32 v[44:45], v[0:1], v[104:105], v[56:57] op_sel_hi:[0,1,1] neg_lo:[1,0,0] neg_hi:[1,0,0]
	v_pk_fma_f32 v[46:47], v[0:1], v[102:103], v[50:51] op_sel_hi:[0,1,1] neg_lo:[1,0,0] neg_hi:[1,0,0]
	v_pk_fma_f32 v[40:41], v[0:1], v[108:109], v[54:55] op_sel_hi:[0,1,1] neg_lo:[1,0,0] neg_hi:[1,0,0]
	v_pk_fma_f32 v[42:43], v[0:1], v[106:107], v[48:49] op_sel_hi:[0,1,1] neg_lo:[1,0,0] neg_hi:[1,0,0]
	v_pk_fma_f32 v[38:39], v[0:1], v[112:113], v[38:39] op_sel_hi:[0,1,1] neg_lo:[1,0,0] neg_hi:[1,0,0]
	v_pk_fma_f32 v[32:33], v[0:1], v[110:111], v[32:33] op_sel_hi:[0,1,1] neg_lo:[1,0,0] neg_hi:[1,0,0]
	v_pk_fma_f32 v[28:29], v[0:1], v[116:117], v[36:37] op_sel_hi:[0,1,1] neg_lo:[1,0,0] neg_hi:[1,0,0]
	v_pk_fma_f32 v[30:31], v[0:1], v[114:115], v[12:13] op_sel_hi:[0,1,1] neg_lo:[1,0,0] neg_hi:[1,0,0]
	v_pk_fma_f32 v[24:25], v[0:1], v[120:121], v[34:35] op_sel_hi:[0,1,1] neg_lo:[1,0,0] neg_hi:[1,0,0]
	v_pk_fma_f32 v[26:27], v[0:1], v[118:119], v[8:9] op_sel_hi:[0,1,1] neg_lo:[1,0,0] neg_hi:[1,0,0]
	v_pk_fma_f32 v[12:13], v[0:1], v[124:125], v[16:17] op_sel_hi:[0,1,1] neg_lo:[1,0,0] neg_hi:[1,0,0]
	v_pk_fma_f32 v[16:17], v[0:1], v[122:123], v[6:7] op_sel_hi:[0,1,1] neg_lo:[1,0,0] neg_hi:[1,0,0]
	v_pk_fma_f32 v[6:7], v[0:1], v[128:129], v[14:15] op_sel_hi:[0,1,1] neg_lo:[1,0,0] neg_hi:[1,0,0]
	v_pk_fma_f32 v[8:9], v[0:1], v[126:127], v[4:5] op_sel_hi:[0,1,1] neg_lo:[1,0,0] neg_hi:[1,0,0]
	s_waitcnt lgkmcnt(0)
	v_pk_fma_f32 v[4:5], v[0:1], v[132:133], v[10:11] op_sel_hi:[0,1,1] neg_lo:[1,0,0] neg_hi:[1,0,0]
	v_pk_fma_f32 v[2:3], v[0:1], v[130:131], v[2:3] op_sel_hi:[0,1,1] neg_lo:[1,0,0] neg_hi:[1,0,0]
	v_add_f32_e32 v0, v144, v145
	v_add_f32_e32 v0, v0, v142
	v_pk_mul_f32 v[148:149], v[80:81], v[80:81]
	v_add_f32_e32 v0, v0, v143
	v_add_f32_e32 v0, v0, v148
	v_pk_mul_f32 v[146:147], v[84:85], v[84:85]
	v_add_f32_e32 v0, v0, v149
	v_add_f32_e32 v0, v0, v146
	v_pk_mul_f32 v[152:153], v[70:71], v[70:71]
	v_add_f32_e32 v0, v0, v147
	v_add_f32_e32 v0, v0, v152
	v_pk_mul_f32 v[150:151], v[82:83], v[82:83]
	v_add_f32_e32 v0, v0, v153
	v_add_f32_e32 v0, v0, v150
	v_pk_mul_f32 v[158:159], v[156:157], v[156:157]
	v_add_f32_e32 v0, v0, v151
	v_add_f32_e32 v0, v0, v158
	v_pk_mul_f32 v[154:155], v[76:77], v[76:77]
	v_add_f32_e32 v0, v0, v159
	v_add_f32_e32 v0, v0, v154
	v_pk_mul_f32 v[164:165], v[66:67], v[66:67]
	v_add_f32_e32 v0, v0, v155
	v_add_f32_e32 v0, v0, v164
	v_pk_mul_f32 v[74:75], v[68:69], v[68:69]
	v_add_f32_e32 v0, v0, v165
	v_add_f32_e32 v0, v0, v74
	v_pk_mul_f32 v[64:65], v[62:63], v[62:63]
	v_add_f32_e32 v0, v0, v75
	v_add_f32_e32 v0, v0, v64
	v_pk_mul_f32 v[72:73], v[60:61], v[60:61]
	v_add_f32_e32 v0, v0, v65
	v_add_f32_e32 v0, v0, v72
	v_pk_mul_f32 v[96:97], v[52:53], v[52:53]
	v_add_f32_e32 v0, v0, v73
	v_add_f32_e32 v0, v0, v96
	v_pk_mul_f32 v[78:79], v[58:59], v[58:59]
	v_add_f32_e32 v0, v0, v97
	v_add_f32_e32 v0, v0, v78
	v_pk_mul_f32 v[50:51], v[46:47], v[46:47]
	v_add_f32_e32 v0, v0, v79
	v_add_f32_e32 v0, v0, v50
	v_pk_mul_f32 v[56:57], v[44:45], v[44:45]
	v_add_f32_e32 v0, v0, v51
	v_add_f32_e32 v0, v0, v56
	v_pk_mul_f32 v[48:49], v[42:43], v[42:43]
	v_add_f32_e32 v0, v0, v57
	v_add_f32_e32 v0, v0, v48
	v_pk_mul_f32 v[54:55], v[40:41], v[40:41]
	v_add_f32_e32 v0, v0, v49
	v_add_f32_e32 v0, v0, v54
	v_pk_mul_f32 v[100:101], v[32:33], v[32:33]
	v_add_f32_e32 v0, v0, v55
	v_add_f32_e32 v0, v0, v100
	v_pk_mul_f32 v[98:99], v[38:39], v[38:39]
	v_add_f32_e32 v0, v0, v101
	v_add_f32_e32 v0, v0, v98
	v_pk_mul_f32 v[102:103], v[30:31], v[30:31]
	v_add_f32_e32 v0, v0, v99
	v_add_f32_e32 v0, v0, v102
	v_pk_mul_f32 v[36:37], v[28:29], v[28:29]
	v_add_f32_e32 v0, v0, v103
	v_add_f32_e32 v0, v0, v36
	v_pk_mul_f32 v[104:105], v[26:27], v[26:27]
	v_add_f32_e32 v0, v0, v37
	v_add_f32_e32 v0, v0, v104
	v_pk_mul_f32 v[34:35], v[24:25], v[24:25]
	v_add_f32_e32 v0, v0, v105
	v_add_f32_e32 v0, v0, v34
	v_pk_mul_f32 v[108:109], v[16:17], v[16:17]
	v_add_f32_e32 v0, v0, v35
	v_add_f32_e32 v0, v0, v108
	v_pk_mul_f32 v[106:107], v[12:13], v[12:13]
	v_add_f32_e32 v0, v0, v109
	v_add_f32_e32 v0, v0, v106
	v_pk_mul_f32 v[110:111], v[8:9], v[8:9]
	v_add_f32_e32 v0, v0, v107
	v_add_f32_e32 v0, v0, v110
	v_pk_mul_f32 v[14:15], v[6:7], v[6:7]
	v_add_f32_e32 v0, v0, v111
	v_add_f32_e32 v0, v0, v14
	v_pk_mul_f32 v[112:113], v[2:3], v[2:3]
	v_add_f32_e32 v0, v0, v15
	v_add_f32_e32 v0, v0, v112
	v_pk_mul_f32 v[10:11], v[4:5], v[4:5]
	v_add_f32_e32 v0, v0, v113
	v_add_f32_e32 v0, v0, v10
	v_pk_mul_f32 v[134:135], v[20:21], v[20:21]
	v_add_f32_e32 v0, v0, v11
	v_add_f32_e32 v0, v0, v134
	v_pk_mul_f32 v[136:137], v[18:19], v[18:19]
	v_add_f32_e32 v0, v0, v135
	v_add_f32_e32 v0, v0, v136
	v_add_f32_e32 v0, v0, v137
	ds_bpermute_b32 v10, v90, v0
	s_waitcnt vmcnt(3)
; DI unsigned pk2(float a, float b) { f32x2 v = {a, b}; bfv2 r = __builtin_convertvector(v, bfv2); return __builtin_bit_cast(unsigned, r); }
; DI float bf_lo(unsigned u) { return __uint_as_float(u << 16); }
; DI float bf_hi(unsigned u) { return __uint_as_float(u & 0xffff0000u); }
; DI void attn_item(const Params& p, int l, int item, char* lds) {
;     ...
;     ss += __shfl_xor(ss, 32);
;     const float rstd = rsqrtf(ss * (1.0f / 128.0f) + 1e-5f) * (1.0f - lam_init);
;     const size_t row = (size_t)(qrow0 + qh * 32 + q);
;     const float* sg = p.subln_g + l * 128;
; #pragma unroll
;     for (int vt = 0; vt < 4; ++vt)
; #pragma unroll
;       for (int e4 = 0; e4 < 4; ++e4) {
;         const int vd = vt * 32 + 8 * e4 + 4 * hh;
;         const u32x2 gu = *(const u32x2*)(p.z + row * NZ + C_GA + h * 128 + vd);
;         const f32x4 gv = *(const f32x4*)(sg + vd);
;         const float y0 = O[vt][4 * e4 + 0] * rstd * gv[0] * bf_lo(gu[0]);
;         const float y1 = O[vt][4 * e4 + 1] * rstd * gv[1] * bf_hi(gu[0]);
;         const float y2 = O[vt][4 * e4 + 2] * rstd * gv[2] * bf_lo(gu[1]);
;         const float y3 = O[vt][4 * e4 + 3] * rstd * gv[3] * bf_hi(gu[1]);
;         u32x2 ov; ov[0] = pk2(y0, y1); ov[1] = pk2(y2, y3);
;         *(u32x2*)(p.o_a + row * 512 + h * 128 + vd) = ov;
;       }
	v_lshlrev_b32_e32 v14, 16, v140
	v_and_b32_e32 v15, 0xffff0000, v140
	v_lshlrev_b64 v[138:139], 10, v[166:167]
	v_lshlrev_b32_e32 v34, 16, v141
	s_waitcnt lgkmcnt(0)
	v_add_f32_e32 v0, v0, v10
	v_mov_b32_e32 v10, 0x3727c5ac
	v_fmamk_f32 v0, v0, 0x3c000000, v10
	v_mul_f32_e32 v10, 0x4b800000, v0
	v_cmp_gt_f32_e32 vcc, s34, v0
	v_and_b32_e32 v35, 0xffff0000, v141
	s_mov_b32 s84, s21
	v_cndmask_b32_e32 v0, v0, v10, vcc
	v_rsq_f32_e32 v0, v0
	v_lshl_add_u64 v[10:11], s[54:55], 0, v[138:139]
	v_lshl_add_u64 v[10:11], v[10:11], 0, s[24:25]
	v_lshl_add_u64 v[10:11], v[10:11], 0, v[168:169]
	v_mul_f32_e32 v36, 0x45800000, v0
	v_cndmask_b32_e32 v0, v0, v36, vcc
	v_mul_f32_e32 v0, v191, v0
	v_pk_mul_f32 v[36:37], v[86:87], v[0:1] op_sel_hi:[1,0]
	v_pk_mul_f32 v[48:49], v[80:81], v[0:1] op_sel_hi:[1,0]
	s_waitcnt vmcnt(2)
	v_pk_mul_f32 v[36:37], v[92:93], v[36:37]
	v_pk_mul_f32 v[50:51], v[82:83], v[0:1] op_sel_hi:[1,0]
	v_pk_mul_f32 v[14:15], v[36:37], v[14:15]
	v_pk_mul_f32 v[36:37], v[88:89], v[0:1] op_sel_hi:[1,0]
	v_cvt_pk_bf16_f32 v14, v14, v15
	v_pk_mul_f32 v[36:37], v[94:95], v[36:37]
	v_pk_mul_f32 v[46:47], v[46:47], v[0:1] op_sel_hi:[1,0]
	v_pk_mul_f32 v[34:35], v[36:37], v[34:35]
	v_pk_mul_f32 v[44:45], v[44:45], v[0:1] op_sel_hi:[1,0]
	v_cvt_pk_bf16_f32 v15, v34, v35
	global_store_dwordx2 v[10:11], v[14:15], off
	global_load_dwordx4 v[214:217], v162, s[22:23] offset:64
	s_nop 0
	global_load_dwordx2 v[226:227], v[22:23], off offset:32
	v_pk_mul_f32 v[42:43], v[42:43], v[0:1] op_sel_hi:[1,0]
	v_pk_mul_f32 v[40:41], v[40:41], v[0:1] op_sel_hi:[1,0]
	v_pk_mul_f32 v[32:33], v[32:33], v[0:1] op_sel_hi:[1,0]
	v_pk_mul_f32 v[38:39], v[38:39], v[0:1] op_sel_hi:[1,0]
	v_pk_mul_f32 v[30:31], v[30:31], v[0:1] op_sel_hi:[1,0]
	v_pk_mul_f32 v[28:29], v[28:29], v[0:1] op_sel_hi:[1,0]
	v_pk_mul_f32 v[26:27], v[26:27], v[0:1] op_sel_hi:[1,0]
	v_pk_mul_f32 v[24:25], v[24:25], v[0:1] op_sel_hi:[1,0]
	v_pk_mul_f32 v[16:17], v[16:17], v[0:1] op_sel_hi:[1,0]
	v_pk_mul_f32 v[12:13], v[12:13], v[0:1] op_sel_hi:[1,0]
	v_pk_mul_f32 v[8:9], v[8:9], v[0:1] op_sel_hi:[1,0]
	v_pk_mul_f32 v[6:7], v[6:7], v[0:1] op_sel_hi:[1,0]
	v_pk_mul_f32 v[2:3], v[2:3], v[0:1] op_sel_hi:[1,0]
	v_pk_mul_f32 v[4:5], v[4:5], v[0:1] op_sel_hi:[1,0]
	s_mov_b32 s85, s26
	s_mov_b32 s86, s27
	s_mov_b32 s87, s30
	s_waitcnt vmcnt(4)
	v_mov_b32_e32 v34, v222
	v_mov_b32_e32 v35, v223
	v_mov_b32_e32 v36, v224
	v_mov_b32_e32 v37, v225
	v_pk_mul_f32 v[34:35], v[34:35], v[48:49]
	s_waitcnt vmcnt(3)
	v_mov_b32_e32 v14, v228
	v_mov_b32_e32 v15, v229
	v_lshlrev_b32_e32 v48, 16, v14
	v_and_b32_e32 v49, 0xffff0000, v14
	v_pk_mul_f32 v[34:35], v[34:35], v[48:49]
	v_pk_mul_f32 v[48:49], v[84:85], v[0:1] op_sel_hi:[1,0]
	v_lshlrev_b32_e32 v14, 16, v15
	v_pk_mul_f32 v[36:37], v[36:37], v[48:49]
	v_and_b32_e32 v15, 0xffff0000, v15
	v_pk_mul_f32 v[14:15], v[36:37], v[14:15]
	v_cvt_pk_bf16_f32 v34, v34, v35
	v_cvt_pk_bf16_f32 v35, v14, v15
	global_store_dwordx2 v[10:11], v[34:35], off offset:16
	global_load_dwordx4 v[222:225], v162, s[22:23] offset:96
	s_nop 0
	global_load_dwordx2 v[228:229], v[22:23], off offset:48
	v_pk_mul_f32 v[48:49], v[70:71], v[0:1] op_sel_hi:[1,0]
	s_waitcnt vmcnt(4)
	v_mov_b32_e32 v34, v214
	v_mov_b32_e32 v35, v215
	v_mov_b32_e32 v36, v216
	v_mov_b32_e32 v37, v217
	v_pk_mul_f32 v[36:37], v[36:37], v[50:51]
	v_pk_mul_f32 v[34:35], v[34:35], v[48:49]
	s_waitcnt vmcnt(3)
	v_mov_b32_e32 v14, v226
	v_mov_b32_e32 v15, v227
	v_lshlrev_b32_e32 v48, 16, v14
	v_and_b32_e32 v49, 0xffff0000, v14
	v_lshlrev_b32_e32 v14, 16, v15
	v_and_b32_e32 v15, 0xffff0000, v15
	v_pk_mul_f32 v[34:35], v[34:35], v[48:49]
	v_pk_mul_f32 v[14:15], v[36:37], v[14:15]
	v_cvt_pk_bf16_f32 v34, v34, v35
	v_cvt_pk_bf16_f32 v35, v14, v15
	global_store_dwordx2 v[10:11], v[34:35], off offset:32
	global_load_dwordx4 v[214:217], v162, s[22:23] offset:128
	s_nop 0
	global_load_dwordx2 v[226:227], v[22:23], off offset:64
	v_pk_mul_f32 v[48:49], v[156:157], v[0:1] op_sel_hi:[1,0]
	v_pk_mul_f32 v[50:51], v[76:77], v[0:1] op_sel_hi:[1,0]
	s_waitcnt vmcnt(4)
	v_mov_b32_e32 v34, v222
	v_mov_b32_e32 v35, v223
	v_mov_b32_e32 v36, v224
	v_mov_b32_e32 v37, v225
	v_pk_mul_f32 v[34:35], v[34:35], v[48:49]
	s_waitcnt vmcnt(3)
	v_mov_b32_e32 v14, v228
	v_mov_b32_e32 v15, v229
	v_lshlrev_b32_e32 v48, 16, v14
	v_and_b32_e32 v49, 0xffff0000, v14
	v_pk_mul_f32 v[36:37], v[36:37], v[50:51]
	v_lshlrev_b32_e32 v14, 16, v15
	v_and_b32_e32 v15, 0xffff0000, v15
	v_pk_mul_f32 v[34:35], v[34:35], v[48:49]
	v_pk_mul_f32 v[14:15], v[36:37], v[14:15]
	v_cvt_pk_bf16_f32 v34, v34, v35
	v_cvt_pk_bf16_f32 v35, v14, v15
	global_store_dwordx2 v[10:11], v[34:35], off offset:48
	global_load_dwordx4 v[222:225], v162, s[22:23] offset:160
	s_nop 0
	global_load_dwordx2 v[228:229], v[22:23], off offset:80
	v_pk_mul_f32 v[48:49], v[66:67], v[0:1] op_sel_hi:[1,0]
	v_pk_mul_f32 v[50:51], v[68:69], v[0:1] op_sel_hi:[1,0]
	s_waitcnt vmcnt(4)
	v_mov_b32_e32 v34, v214
	v_mov_b32_e32 v35, v215
	v_mov_b32_e32 v36, v216
	v_mov_b32_e32 v37, v217
	v_pk_mul_f32 v[34:35], v[48:49], v[34:35]
	s_waitcnt vmcnt(3)
	v_mov_b32_e32 v14, v226
	v_mov_b32_e32 v15, v227
	v_lshlrev_b32_e32 v48, 16, v14
	v_and_b32_e32 v49, 0xffff0000, v14
	v_pk_mul_f32 v[36:37], v[50:51], v[36:37]
	v_lshlrev_b32_e32 v14, 16, v15
	v_and_b32_e32 v15, 0xffff0000, v15
	v_pk_mul_f32 v[34:35], v[34:35], v[48:49]
	v_pk_mul_f32 v[14:15], v[36:37], v[14:15]
	v_cvt_pk_bf16_f32 v34, v34, v35
	v_cvt_pk_bf16_f32 v35, v14, v15
	global_store_dwordx2 v[10:11], v[34:35], off offset:64
	global_load_dwordx4 v[214:217], v162, s[22:23] offset:192
	s_nop 0
	global_load_dwordx2 v[226:227], v[22:23], off offset:96
	v_pk_mul_f32 v[48:49], v[62:63], v[0:1] op_sel_hi:[1,0]
	v_pk_mul_f32 v[50:51], v[60:61], v[0:1] op_sel_hi:[1,0]
	s_waitcnt vmcnt(4)
; DI unsigned pk2(float a, float b) { f32x2 v = {a, b}; bfv2 r = __builtin_convertvector(v, bfv2); return __builtin_bit_cast(unsigned, r); }
; DI float bf_lo(unsigned u) { return __uint_as_float(u << 16); }
; DI float bf_hi(unsigned u) { return __uint_as_float(u & 0xffff0000u); }
; DI void attn_item(const Params& p, int l, int item, char* lds) {
;     ...
; #pragma unroll
;     for (int vt = 0; vt < 4; ++vt)
; #pragma unroll
;       for (int e4 = 0; e4 < 4; ++e4) {
;         const int vd = vt * 32 + 8 * e4 + 4 * hh;
;         const u32x2 gu = *(const u32x2*)(p.z + row * NZ + C_GA + h * 128 + vd);
;         const f32x4 gv = *(const f32x4*)(sg + vd);
;         const float y0 = O[vt][4 * e4 + 0] * rstd * gv[0] * bf_lo(gu[0]);
;         const float y1 = O[vt][4 * e4 + 1] * rstd * gv[1] * bf_hi(gu[0]);
;         const float y2 = O[vt][4 * e4 + 2] * rstd * gv[2] * bf_lo(gu[1]);
;         const float y3 = O[vt][4 * e4 + 3] * rstd * gv[3] * bf_hi(gu[1]);
;         u32x2 ov; ov[0] = pk2(y0, y1); ov[1] = pk2(y2, y3);
;         *(u32x2*)(p.o_a + row * 512 + h * 128 + vd) = ov;
;       }
	v_mov_b32_e32 v34, v222
	v_mov_b32_e32 v35, v223
	v_mov_b32_e32 v36, v224
	v_mov_b32_e32 v37, v225
	v_pk_mul_f32 v[34:35], v[48:49], v[34:35]
	s_waitcnt vmcnt(3)
	v_mov_b32_e32 v14, v228
	v_mov_b32_e32 v15, v229
	v_lshlrev_b32_e32 v48, 16, v14
	v_and_b32_e32 v49, 0xffff0000, v14
	v_pk_mul_f32 v[36:37], v[50:51], v[36:37]
	v_lshlrev_b32_e32 v14, 16, v15
	v_and_b32_e32 v15, 0xffff0000, v15
	v_pk_mul_f32 v[34:35], v[34:35], v[48:49]
	v_pk_mul_f32 v[14:15], v[36:37], v[14:15]
	v_cvt_pk_bf16_f32 v34, v34, v35
	v_cvt_pk_bf16_f32 v35, v14, v15
	global_store_dwordx2 v[10:11], v[34:35], off offset:80
	global_load_dwordx4 v[222:225], v162, s[22:23] offset:224
	s_nop 0
	global_load_dwordx2 v[228:229], v[22:23], off offset:112
	v_pk_mul_f32 v[48:49], v[52:53], v[0:1] op_sel_hi:[1,0]
	v_pk_mul_f32 v[50:51], v[58:59], v[0:1] op_sel_hi:[1,0]
	s_waitcnt vmcnt(4)
	v_mov_b32_e32 v34, v214
	v_mov_b32_e32 v35, v215
	v_mov_b32_e32 v36, v216
	v_mov_b32_e32 v37, v217
	v_pk_mul_f32 v[34:35], v[48:49], v[34:35]
	s_waitcnt vmcnt(3)
	v_mov_b32_e32 v14, v226
	v_mov_b32_e32 v15, v227
	v_lshlrev_b32_e32 v48, 16, v14
	v_and_b32_e32 v49, 0xffff0000, v14
	v_pk_mul_f32 v[36:37], v[50:51], v[36:37]
	v_lshlrev_b32_e32 v14, 16, v15
	v_and_b32_e32 v15, 0xffff0000, v15
	v_pk_mul_f32 v[34:35], v[34:35], v[48:49]
	v_pk_mul_f32 v[14:15], v[36:37], v[14:15]
	v_cvt_pk_bf16_f32 v34, v34, v35
	v_cvt_pk_bf16_f32 v35, v14, v15
	global_store_dwordx2 v[10:11], v[34:35], off offset:96
	global_load_dwordx4 v[214:217], v162, s[22:23] offset:256
	s_nop 0
	global_load_dwordx2 v[226:227], v[22:23], off offset:128
	s_waitcnt vmcnt(4)
	v_mov_b32_e32 v34, v222
	v_mov_b32_e32 v35, v223
	v_mov_b32_e32 v36, v224
	v_mov_b32_e32 v37, v225
	v_pk_mul_f32 v[34:35], v[46:47], v[34:35]
	s_waitcnt vmcnt(3)
	v_mov_b32_e32 v14, v228
	v_mov_b32_e32 v15, v229
	v_lshlrev_b32_e32 v46, 16, v14
	v_and_b32_e32 v47, 0xffff0000, v14
	v_pk_mul_f32 v[36:37], v[44:45], v[36:37]
	v_lshlrev_b32_e32 v14, 16, v15
	v_and_b32_e32 v15, 0xffff0000, v15
	v_pk_mul_f32 v[34:35], v[34:35], v[46:47]
	v_pk_mul_f32 v[14:15], v[36:37], v[14:15]
	v_cvt_pk_bf16_f32 v34, v34, v35
	v_cvt_pk_bf16_f32 v35, v14, v15
	global_store_dwordx2 v[10:11], v[34:35], off offset:112
	global_load_dwordx4 v[222:225], v162, s[22:23] offset:288
	s_nop 0
	global_load_dwordx2 v[228:229], v[22:23], off offset:144
	s_waitcnt vmcnt(4)
	v_mov_b32_e32 v34, v214
	v_mov_b32_e32 v35, v215
	v_mov_b32_e32 v36, v216
	v_mov_b32_e32 v37, v217
	v_pk_mul_f32 v[34:35], v[42:43], v[34:35]
	s_waitcnt vmcnt(3)
	v_mov_b32_e32 v14, v226
	v_mov_b32_e32 v15, v227
	v_lshlrev_b32_e32 v42, 16, v14
	v_and_b32_e32 v43, 0xffff0000, v14
	v_pk_mul_f32 v[36:37], v[40:41], v[36:37]
	v_lshlrev_b32_e32 v14, 16, v15
	v_and_b32_e32 v15, 0xffff0000, v15
	v_pk_mul_f32 v[34:35], v[34:35], v[42:43]
	v_pk_mul_f32 v[14:15], v[36:37], v[14:15]
	v_cvt_pk_bf16_f32 v34, v34, v35
	v_cvt_pk_bf16_f32 v35, v14, v15
	global_store_dwordx2 v[10:11], v[34:35], off offset:128
	global_load_dwordx4 v[214:217], v162, s[22:23] offset:320
	s_nop 0
	global_load_dwordx2 v[226:227], v[22:23], off offset:160
	s_waitcnt vmcnt(4)
	v_mov_b32_e32 v34, v222
	v_mov_b32_e32 v35, v223
	v_mov_b32_e32 v36, v224
	v_mov_b32_e32 v37, v225
	v_pk_mul_f32 v[32:33], v[32:33], v[34:35]
	s_waitcnt vmcnt(3)
	v_mov_b32_e32 v14, v228
	v_mov_b32_e32 v15, v229
	v_lshlrev_b32_e32 v34, 16, v14
	v_and_b32_e32 v35, 0xffff0000, v14
	v_pk_mul_f32 v[36:37], v[38:39], v[36:37]
	v_lshlrev_b32_e32 v14, 16, v15
	v_and_b32_e32 v15, 0xffff0000, v15
	v_pk_mul_f32 v[32:33], v[32:33], v[34:35]
	v_pk_mul_f32 v[14:15], v[36:37], v[14:15]
	v_cvt_pk_bf16_f32 v32, v32, v33
	v_cvt_pk_bf16_f32 v33, v14, v15
	global_store_dwordx2 v[10:11], v[32:33], off offset:144
	global_load_dwordx4 v[222:225], v162, s[22:23] offset:352
	s_nop 0
	global_load_dwordx2 v[228:229], v[22:23], off offset:176
	s_waitcnt vmcnt(4)
	v_mov_b32_e32 v32, v214
	v_mov_b32_e32 v33, v215
	v_mov_b32_e32 v34, v216
	v_mov_b32_e32 v35, v217
	v_pk_mul_f32 v[30:31], v[30:31], v[32:33]
	s_waitcnt vmcnt(3)
; DI unsigned pk2(float a, float b) { f32x2 v = {a, b}; bfv2 r = __builtin_convertvector(v, bfv2); return __builtin_bit_cast(unsigned, r); }
; DI float bf_lo(unsigned u) { return __uint_as_float(u << 16); }
; DI float bf_hi(unsigned u) { return __uint_as_float(u & 0xffff0000u); }
; DI void attn_item(const Params& p, int l, int item, char* lds) {
;     ...
;     const float* sg = p.subln_g + l * 128;
; #pragma unroll
;     for (int vt = 0; vt < 4; ++vt)
; #pragma unroll
;       for (int e4 = 0; e4 < 4; ++e4) {
;         const int vd = vt * 32 + 8 * e4 + 4 * hh;
;         const u32x2 gu = *(const u32x2*)(p.z + row * NZ + C_GA + h * 128 + vd);
;         const f32x4 gv = *(const f32x4*)(sg + vd);
;         const float y0 = O[vt][4 * e4 + 0] * rstd * gv[0] * bf_lo(gu[0]);
;         const float y1 = O[vt][4 * e4 + 1] * rstd * gv[1] * bf_hi(gu[0]);
;         const float y2 = O[vt][4 * e4 + 2] * rstd * gv[2] * bf_lo(gu[1]);
;         const float y3 = O[vt][4 * e4 + 3] * rstd * gv[3] * bf_hi(gu[1]);
;         u32x2 ov; ov[0] = pk2(y0, y1); ov[1] = pk2(y2, y3);
;         *(u32x2*)(p.o_a + row * 512 + h * 128 + vd) = ov;
;       }
	v_mov_b32_e32 v14, v226
	v_mov_b32_e32 v15, v227
	v_lshlrev_b32_e32 v32, 16, v14
	v_and_b32_e32 v33, 0xffff0000, v14
	v_pk_mul_f32 v[28:29], v[28:29], v[34:35]
	v_lshlrev_b32_e32 v14, 16, v15
	v_and_b32_e32 v15, 0xffff0000, v15
	v_pk_mul_f32 v[30:31], v[30:31], v[32:33]
	v_pk_mul_f32 v[14:15], v[28:29], v[14:15]
	v_cvt_pk_bf16_f32 v28, v30, v31
	v_cvt_pk_bf16_f32 v29, v14, v15
	global_store_dwordx2 v[10:11], v[28:29], off offset:160
	global_load_dwordx4 v[214:217], v162, s[22:23] offset:384
	s_nop 0
	global_load_dwordx2 v[226:227], v[22:23], off offset:192
	s_waitcnt vmcnt(4)
	v_mov_b32_e32 v28, v222
	v_mov_b32_e32 v29, v223
	v_mov_b32_e32 v30, v224
	v_mov_b32_e32 v31, v225
	v_pk_mul_f32 v[26:27], v[26:27], v[28:29]
	s_waitcnt vmcnt(3)
	v_mov_b32_e32 v14, v228
	v_mov_b32_e32 v15, v229
	v_lshlrev_b32_e32 v28, 16, v14
	v_and_b32_e32 v29, 0xffff0000, v14
	v_pk_mul_f32 v[24:25], v[24:25], v[30:31]
	v_lshlrev_b32_e32 v14, 16, v15
	v_and_b32_e32 v15, 0xffff0000, v15
	v_pk_mul_f32 v[26:27], v[26:27], v[28:29]
	v_pk_mul_f32 v[14:15], v[24:25], v[14:15]
	v_cvt_pk_bf16_f32 v24, v26, v27
	v_cvt_pk_bf16_f32 v25, v14, v15
	global_store_dwordx2 v[10:11], v[24:25], off offset:176
	global_load_dwordx4 v[222:225], v162, s[22:23] offset:416
	s_nop 0
	global_load_dwordx2 v[228:229], v[22:23], off offset:208
	s_waitcnt vmcnt(4)
	v_mov_b32_e32 v24, v214
	v_mov_b32_e32 v25, v215
	v_mov_b32_e32 v26, v216
	v_mov_b32_e32 v27, v217
	v_pk_mul_f32 v[16:17], v[16:17], v[24:25]
	s_waitcnt vmcnt(3)
	v_mov_b32_e32 v14, v226
	v_mov_b32_e32 v15, v227
	v_lshlrev_b32_e32 v24, 16, v14
	v_and_b32_e32 v25, 0xffff0000, v14
	v_pk_mul_f32 v[12:13], v[12:13], v[26:27]
	v_lshlrev_b32_e32 v14, 16, v15
	v_and_b32_e32 v15, 0xffff0000, v15
	v_pk_mul_f32 v[16:17], v[16:17], v[24:25]
	v_pk_mul_f32 v[12:13], v[12:13], v[14:15]
	v_cvt_pk_bf16_f32 v14, v16, v17
	v_cvt_pk_bf16_f32 v15, v12, v13
	global_store_dwordx2 v[10:11], v[14:15], off offset:192
	global_load_dwordx4 v[214:217], v162, s[22:23] offset:448
	s_nop 0
	global_load_dwordx2 v[226:227], v[22:23], off offset:224
	s_waitcnt vmcnt(4)
	v_mov_b32_e32 v12, v222
	v_mov_b32_e32 v13, v223
	v_mov_b32_e32 v14, v224
	v_mov_b32_e32 v15, v225
	v_pk_mul_f32 v[8:9], v[8:9], v[12:13]
	s_waitcnt vmcnt(3)
	v_mov_b32_e32 v16, v228
	v_mov_b32_e32 v17, v229
	v_lshlrev_b32_e32 v12, 16, v16
	v_and_b32_e32 v13, 0xffff0000, v16
	v_pk_mul_f32 v[6:7], v[6:7], v[14:15]
	v_lshlrev_b32_e32 v14, 16, v17
	v_and_b32_e32 v15, 0xffff0000, v17
	v_pk_mul_f32 v[8:9], v[8:9], v[12:13]
	v_pk_mul_f32 v[6:7], v[6:7], v[14:15]
	v_cvt_pk_bf16_f32 v8, v8, v9
	v_cvt_pk_bf16_f32 v9, v6, v7
	global_store_dwordx2 v[10:11], v[8:9], off offset:208
	global_load_dwordx4 v[222:225], v162, s[22:23] offset:480
	s_nop 0
	global_load_dwordx2 v[228:229], v[22:23], off offset:240
	s_waitcnt vmcnt(4)
	v_mov_b32_e32 v6, v214
	v_mov_b32_e32 v7, v215
	v_mov_b32_e32 v8, v216
	v_mov_b32_e32 v9, v217
	v_pk_mul_f32 v[2:3], v[2:3], v[6:7]
	s_waitcnt vmcnt(3)
	v_mov_b32_e32 v12, v226
	v_mov_b32_e32 v13, v227
	v_lshlrev_b32_e32 v6, 16, v12
	v_and_b32_e32 v7, 0xffff0000, v12
	v_pk_mul_f32 v[4:5], v[4:5], v[8:9]
	v_lshlrev_b32_e32 v8, 16, v13
	v_and_b32_e32 v9, 0xffff0000, v13
	v_pk_mul_f32 v[2:3], v[2:3], v[6:7]
	v_pk_mul_f32 v[4:5], v[4:5], v[8:9]
	v_cvt_pk_bf16_f32 v2, v2, v3
	v_cvt_pk_bf16_f32 v3, v4, v5
	global_store_dwordx2 v[10:11], v[2:3], off offset:224
	s_nop 0
	v_pk_mul_f32 v[8:9], v[20:21], v[0:1] op_sel_hi:[1,0]
	v_pk_mul_f32 v[12:13], v[18:19], v[0:1] op_sel_hi:[1,0]
	s_waitcnt vmcnt(2)
	v_mov_b32_e32 v2, v222
	v_mov_b32_e32 v3, v223
	v_mov_b32_e32 v4, v224
	v_mov_b32_e32 v5, v225
	v_pk_mul_f32 v[2:3], v[8:9], v[2:3]
	s_waitcnt vmcnt(1)
	v_mov_b32_e32 v6, v228
	v_mov_b32_e32 v7, v229
	v_lshlrev_b32_e32 v8, 16, v6
	v_and_b32_e32 v9, 0xffff0000, v6
	v_pk_mul_f32 v[4:5], v[12:13], v[4:5]
	v_lshlrev_b32_e32 v6, 16, v7
	v_and_b32_e32 v7, 0xffff0000, v7
	v_pk_mul_f32 v[2:3], v[2:3], v[8:9]
	v_pk_mul_f32 v[4:5], v[4:5], v[6:7]
	v_cvt_pk_bf16_f32 v2, v2, v3
	v_cvt_pk_bf16_f32 v3, v4, v5
	global_store_dwordx2 v[10:11], v[2:3], off offset:240
	s_branch .LBB0_571
